# grid barrier: non-leader workgroups invalidate L1 before polling for the release; P12 epilogue max(0,x) without the canonicalising self-max (store-data WAR pads added)
# speedup vs baseline: 1.0366x; 1.0336x over previous
.LBB0_52:
	s_or_b64 exec, exec, s[50:51]
	v_cvt_f32_u32_e32 v4, v2
	s_waitcnt vmcnt(0)
	v_readfirstlane_b32 s5, v3
	v_sub_u32_e32 v3, 0, v2
	v_rcp_iflag_f32_e32 v4, v4
	v_add_u32_e32 v5, s5, v1
	v_mul_f32_e32 v4, 0x4f7ffffe, v4
	v_cvt_u32_f32_e32 v4, v4
	v_mul_lo_u32 v1, v3, v4
	v_mul_hi_u32 v1, v4, v1
	v_add_u32_e32 v1, v4, v1
	v_mul_hi_u32 v1, v5, v1
	v_mul_lo_u32 v3, v1, v2
	v_sub_u32_e32 v3, v5, v3
	v_add_u32_e32 v4, 1, v1
	v_cmp_ge_u32_e32 vcc, v3, v2
	s_nop 1
	v_cndmask_b32_e32 v1, v1, v4, vcc
	v_sub_u32_e32 v4, v3, v2
	v_cndmask_b32_e32 v3, v3, v4, vcc
	v_add_u32_e32 v4, 1, v1
	v_cmp_ge_u32_e32 vcc, v3, v2
	v_add_u32_e32 v3, 1, v5
	s_nop 0
	v_cndmask_b32_e32 v1, v1, v4, vcc
	v_mul_lo_u32 v4, v2, v1
	v_add_u32_e32 v2, v4, v2
	v_cmp_ne_u32_e32 vcc, v3, v2
	s_and_saveexec_b64 s[24:25], vcc
	s_xor_b64 s[48:49], exec, s[24:25]
	s_cbranch_execz .LBB0_66
	s_waitcnt lgkmcnt(0)
	v_mov_b32_e32 v0, 0x2000
	buffer_inv sc1
	global_load_dword v0, v0, s[46:47] offset:1024 sc1
	s_add_u32 s54, s46, 0x2400
	s_addc_u32 s55, s47, 0
	s_waitcnt vmcnt(0)
	v_cmp_eq_u32_e32 vcc, v0, v1
	s_and_saveexec_b64 s[50:51], vcc
	s_cbranch_execz .LBB0_65
	s_add_u32 s52, s44, 0x4200
	s_addc_u32 s53, s45, 0
	s_mov_b32 s5, 1
	s_mov_b64 s[56:57], 0
	v_mov_b32_e32 v0, 0
	s_branch .LBB0_56

.LBB0_65:
	s_or_b64 exec, exec, s[50:51]
	s_waitcnt vmcnt(0)
	s_waitcnt vmcnt(0)

.LBB0_175:
	s_or_b64 exec, exec, s[14:15]
	v_cvt_f32_u32_e32 v4, v2
	s_waitcnt vmcnt(0)
	v_readfirstlane_b32 s12, v3
	v_sub_u32_e32 v3, 0, v2
	v_rcp_iflag_f32_e32 v4, v4
	v_add_u32_e32 v5, s12, v1
	v_mul_f32_e32 v4, 0x4f7ffffe, v4
	v_cvt_u32_f32_e32 v4, v4
	v_mul_lo_u32 v1, v3, v4
	v_mul_hi_u32 v1, v4, v1
	v_add_u32_e32 v1, v4, v1
	v_mul_hi_u32 v1, v5, v1
	v_mul_lo_u32 v3, v1, v2
	v_sub_u32_e32 v3, v5, v3
	v_add_u32_e32 v4, 1, v1
	v_cmp_ge_u32_e32 vcc, v3, v2
	s_nop 1
	v_cndmask_b32_e32 v1, v1, v4, vcc
	v_sub_u32_e32 v4, v3, v2
	v_cndmask_b32_e32 v3, v3, v4, vcc
	v_add_u32_e32 v4, 1, v1
	v_cmp_ge_u32_e32 vcc, v3, v2
	v_add_u32_e32 v3, 1, v5
	s_nop 0
	v_cndmask_b32_e32 v1, v1, v4, vcc
	v_mul_lo_u32 v4, v2, v1
	v_add_u32_e32 v2, v4, v2
	v_cmp_ne_u32_e32 vcc, v3, v2
	s_and_saveexec_b64 s[12:13], vcc
	s_xor_b64 s[12:13], exec, s[12:13]
	s_cbranch_execz .LBB0_189
	s_waitcnt lgkmcnt(0)
	v_mov_b32_e32 v0, 0x2000
	buffer_inv sc1
	global_load_dword v0, v0, s[10:11] offset:1024 sc1
	s_add_u32 s18, s10, 0x2400
	s_addc_u32 s19, s11, 0
	s_waitcnt vmcnt(0)
	v_cmp_eq_u32_e32 vcc, v0, v1
	s_and_saveexec_b64 s[14:15], vcc
	s_cbranch_execz .LBB0_188
	s_add_u32 s16, s8, 0x4200
	s_addc_u32 s17, s9, 0
	s_mov_b32 s24, 1
	s_mov_b64 s[20:21], 0
	v_mov_b32_e32 v0, 0
	s_branch .LBB0_179

.LBB0_188:
	s_or_b64 exec, exec, s[14:15]
	s_waitcnt vmcnt(0)
	s_waitcnt vmcnt(0)

.LBB0_271:
	s_or_b64 exec, exec, s[12:13]
	v_cvt_f32_u32_e32 v4, v2
	s_waitcnt vmcnt(0)
	v_readfirstlane_b32 s10, v3
	v_sub_u32_e32 v3, 0, v2
	v_rcp_iflag_f32_e32 v4, v4
	v_add_u32_e32 v5, s10, v1
	v_mul_f32_e32 v4, 0x4f7ffffe, v4
	v_cvt_u32_f32_e32 v4, v4
	v_mul_lo_u32 v1, v3, v4
	v_mul_hi_u32 v1, v4, v1
	v_add_u32_e32 v1, v4, v1
	v_mul_hi_u32 v1, v5, v1
	v_mul_lo_u32 v3, v1, v2
	v_sub_u32_e32 v3, v5, v3
	v_add_u32_e32 v4, 1, v1
	v_cmp_ge_u32_e32 vcc, v3, v2
	s_nop 1
	v_cndmask_b32_e32 v1, v1, v4, vcc
	v_sub_u32_e32 v4, v3, v2
	v_cndmask_b32_e32 v3, v3, v4, vcc
	v_add_u32_e32 v4, 1, v1
	v_cmp_ge_u32_e32 vcc, v3, v2
	v_add_u32_e32 v3, 1, v5
	s_nop 0
	v_cndmask_b32_e32 v1, v1, v4, vcc
	v_mul_lo_u32 v4, v2, v1
	v_add_u32_e32 v2, v4, v2
	v_cmp_ne_u32_e32 vcc, v3, v2
	s_and_saveexec_b64 s[10:11], vcc
	s_xor_b64 s[10:11], exec, s[10:11]
	s_cbranch_execz .LBB0_285
	s_waitcnt lgkmcnt(0)
	v_mov_b32_e32 v0, 0x2000
	buffer_inv sc1
	global_load_dword v0, v0, s[8:9] offset:1024 sc1
	s_add_u32 s16, s8, 0x2400
	s_addc_u32 s17, s9, 0
	s_waitcnt vmcnt(0)
	v_cmp_eq_u32_e32 vcc, v0, v1
	s_and_saveexec_b64 s[12:13], vcc
	s_cbranch_execz .LBB0_284
	s_add_u32 s14, s6, 0x4200
	s_addc_u32 s15, s7, 0
	s_mov_b32 s24, 1
	s_mov_b64 s[18:19], 0
	v_mov_b32_e32 v0, 0
	s_branch .LBB0_275

.LBB0_284:
	s_or_b64 exec, exec, s[12:13]
	s_waitcnt vmcnt(0)
	s_waitcnt vmcnt(0)

.LBB0_1473:
	v_lshl_add_u32 v152, s36, 8, v146
	v_lshl_or_b32 v144, s58, 8, v148
	v_max_f32_e32 v120, 0, v120
	v_ashrrev_i32_e32 v145, 31, v144
	v_ashrrev_i32_e32 v153, 31, v152
	v_max_f32_e32 v121, 0, v121
	v_max_f32_e32 v122, 0, v122
	v_lshl_add_u64 v[154:155], v[144:145], 1, s[8:9]
	v_lshlrev_b64 v[144:145], 14, v[152:153]
	v_mul_f32_e32 v153, v120, v120
	v_max_f32_e32 v120, 0, v125
	v_max_f32_e32 v124, 0, v124
	v_mul_f32_e32 v125, v121, v121
	v_max_f32_e32 v121, 0, v126
	v_mul_f32_e32 v126, v122, v122
	v_max_f32_e32 v122, 0, v127
	v_max_f32_e32 v123, 0, v123
	v_mul_f32_e32 v120, v120, v120
	v_max_f32_e32 v112, 0, v112
	v_max_f32_e32 v113, 0, v113
	v_max_f32_e32 v114, 0, v114
	v_lshl_add_u64 v[144:145], v[154:155], 0, v[144:145]
	v_mul_f32_e32 v124, v124, v124
	v_mul_f32_e32 v121, v121, v121
	v_mul_f32_e32 v122, v122, v122
	v_mul_f32_e32 v123, v123, v123
	v_cvt_pk_bf16_f32 v120, v124, v120
	v_cvt_pk_bf16_f32 v121, v121, v122
	v_cvt_pk_bf16_f32 v122, v153, v125
	v_cvt_pk_bf16_f32 v123, v126, v123
	global_store_dwordx4 v[144:145], v[120:123], off
	v_max_f32_e32 v116, 0, v116
	v_max_f32_e32 v115, 0, v115
	v_mul_f32_e32 v120, v112, v112
	v_max_f32_e32 v112, 0, v117
	v_mul_f32_e32 v117, v113, v113
	v_max_f32_e32 v113, 0, v118
	v_mul_f32_e32 v118, v114, v114
	v_max_f32_e32 v114, 0, v119
	v_mul_f32_e32 v112, v112, v112
	v_mul_f32_e32 v113, v113, v113
	v_mul_f32_e32 v114, v114, v114
	v_max_f32_e32 v104, 0, v104
	v_mul_f32_e32 v116, v116, v116
	v_mul_f32_e32 v115, v115, v115
	v_cvt_pk_bf16_f32 v112, v116, v112
	v_cvt_pk_bf16_f32 v113, v113, v114
	v_cvt_pk_bf16_f32 v114, v120, v117
	v_max_f32_e32 v105, 0, v105
	v_max_f32_e32 v106, 0, v106
	v_cvt_pk_bf16_f32 v115, v118, v115
	global_store_dwordx4 v[144:145], v[112:115], off offset:256
	s_nop 1
	v_or_b32_e32 v112, 16, v152
	v_mul_f32_e32 v114, v104, v104
	v_max_f32_e32 v104, 0, v109
	v_ashrrev_i32_e32 v113, 31, v112
	v_max_f32_e32 v108, 0, v108
	v_mul_f32_e32 v109, v105, v105
	v_max_f32_e32 v105, 0, v110
	v_mul_f32_e32 v110, v106, v106
	v_max_f32_e32 v106, 0, v111
	v_max_f32_e32 v107, 0, v107
	v_lshlrev_b64 v[112:113], 14, v[112:113]
	v_mul_f32_e32 v104, v104, v104
	v_max_f32_e32 v96, 0, v96
	v_max_f32_e32 v97, 0, v97
	v_max_f32_e32 v98, 0, v98
	v_lshl_add_u64 v[112:113], v[154:155], 0, v[112:113]
	v_mul_f32_e32 v108, v108, v108
	v_mul_f32_e32 v105, v105, v105
	v_mul_f32_e32 v106, v106, v106
	v_mul_f32_e32 v107, v107, v107
	v_cvt_pk_bf16_f32 v104, v108, v104
	v_cvt_pk_bf16_f32 v105, v105, v106
	v_cvt_pk_bf16_f32 v106, v114, v109
	v_cvt_pk_bf16_f32 v107, v110, v107
	global_store_dwordx4 v[112:113], v[104:107], off
	v_max_f32_e32 v100, 0, v100
	v_max_f32_e32 v99, 0, v99
	v_mul_f32_e32 v104, v96, v96
	v_max_f32_e32 v96, 0, v101
	v_mul_f32_e32 v101, v97, v97
	v_max_f32_e32 v97, 0, v102
	v_mul_f32_e32 v102, v98, v98
	v_max_f32_e32 v98, 0, v103
	v_mul_f32_e32 v96, v96, v96
	v_mul_f32_e32 v97, v97, v97
	v_mul_f32_e32 v98, v98, v98
	v_max_f32_e32 v88, 0, v88
	v_mul_f32_e32 v100, v100, v100
	v_mul_f32_e32 v99, v99, v99
	v_cvt_pk_bf16_f32 v96, v100, v96
	v_cvt_pk_bf16_f32 v97, v97, v98
	v_cvt_pk_bf16_f32 v98, v104, v101
	v_max_f32_e32 v89, 0, v89
	v_max_f32_e32 v90, 0, v90
	v_cvt_pk_bf16_f32 v99, v102, v99
	global_store_dwordx4 v[112:113], v[96:99], off offset:256
	s_nop 1
	v_or_b32_e32 v96, 32, v152
	v_mul_f32_e32 v98, v88, v88
	v_max_f32_e32 v88, 0, v93
	v_ashrrev_i32_e32 v97, 31, v96
	v_max_f32_e32 v92, 0, v92
	v_mul_f32_e32 v93, v89, v89
	v_max_f32_e32 v89, 0, v94
	v_mul_f32_e32 v94, v90, v90
	v_max_f32_e32 v90, 0, v95
	v_max_f32_e32 v91, 0, v91
	v_lshlrev_b64 v[96:97], 14, v[96:97]
	v_mul_f32_e32 v88, v88, v88
	v_max_f32_e32 v80, 0, v80
	v_max_f32_e32 v81, 0, v81
	v_max_f32_e32 v82, 0, v82
	v_lshl_add_u64 v[96:97], v[154:155], 0, v[96:97]
	v_mul_f32_e32 v92, v92, v92
	v_mul_f32_e32 v89, v89, v89
	v_mul_f32_e32 v90, v90, v90
	v_mul_f32_e32 v91, v91, v91
	v_cvt_pk_bf16_f32 v88, v92, v88
	v_cvt_pk_bf16_f32 v89, v89, v90
	v_cvt_pk_bf16_f32 v90, v98, v93
	v_cvt_pk_bf16_f32 v91, v94, v91
	global_store_dwordx4 v[96:97], v[88:91], off
	v_max_f32_e32 v84, 0, v84
	v_max_f32_e32 v83, 0, v83
	v_mul_f32_e32 v88, v80, v80
	v_max_f32_e32 v80, 0, v85
	v_mul_f32_e32 v85, v81, v81
	v_max_f32_e32 v81, 0, v86
	v_mul_f32_e32 v86, v82, v82
	v_max_f32_e32 v82, 0, v87
	v_mul_f32_e32 v80, v80, v80
	v_mul_f32_e32 v81, v81, v81
	v_mul_f32_e32 v82, v82, v82
	v_max_f32_e32 v72, 0, v72
	v_mul_f32_e32 v84, v84, v84
	v_mul_f32_e32 v83, v83, v83
	v_cvt_pk_bf16_f32 v80, v84, v80
	v_cvt_pk_bf16_f32 v81, v81, v82
	v_cvt_pk_bf16_f32 v82, v88, v85
	v_max_f32_e32 v73, 0, v73
	v_max_f32_e32 v74, 0, v74
	v_cvt_pk_bf16_f32 v83, v86, v83
	global_store_dwordx4 v[96:97], v[80:83], off offset:256
	s_nop 1
	v_or_b32_e32 v80, 48, v152
	v_mul_f32_e32 v82, v72, v72
	v_max_f32_e32 v72, 0, v77
	v_ashrrev_i32_e32 v81, 31, v80
	v_max_f32_e32 v76, 0, v76
	v_mul_f32_e32 v77, v73, v73
	v_max_f32_e32 v73, 0, v78
	v_mul_f32_e32 v78, v74, v74
	v_max_f32_e32 v74, 0, v79
	v_max_f32_e32 v75, 0, v75
	v_lshlrev_b64 v[80:81], 14, v[80:81]
	v_mul_f32_e32 v72, v72, v72
	v_max_f32_e32 v64, 0, v64
	v_max_f32_e32 v65, 0, v65
	v_max_f32_e32 v66, 0, v66
	v_lshl_add_u64 v[80:81], v[154:155], 0, v[80:81]
	v_mul_f32_e32 v76, v76, v76
	v_mul_f32_e32 v73, v73, v73
	v_mul_f32_e32 v74, v74, v74
	v_mul_f32_e32 v75, v75, v75
	v_cvt_pk_bf16_f32 v72, v76, v72
	v_cvt_pk_bf16_f32 v73, v73, v74
	v_cvt_pk_bf16_f32 v74, v82, v77
	v_cvt_pk_bf16_f32 v75, v78, v75
	global_store_dwordx4 v[80:81], v[72:75], off
	v_max_f32_e32 v68, 0, v68
	v_max_f32_e32 v67, 0, v67
	v_mul_f32_e32 v72, v64, v64
	v_max_f32_e32 v64, 0, v69
	v_mul_f32_e32 v69, v65, v65
	v_max_f32_e32 v65, 0, v70
	v_mul_f32_e32 v70, v66, v66
	v_max_f32_e32 v66, 0, v71
	v_mul_f32_e32 v64, v64, v64
	v_mul_f32_e32 v65, v65, v65
	v_mul_f32_e32 v66, v66, v66
	v_max_f32_e32 v56, 0, v56
	v_mul_f32_e32 v68, v68, v68
	v_mul_f32_e32 v67, v67, v67
	v_cvt_pk_bf16_f32 v64, v68, v64
	v_cvt_pk_bf16_f32 v65, v65, v66
	v_cvt_pk_bf16_f32 v66, v72, v69
	v_max_f32_e32 v57, 0, v57
	v_max_f32_e32 v58, 0, v58
	v_cvt_pk_bf16_f32 v67, v70, v67
	global_store_dwordx4 v[80:81], v[64:67], off offset:256
	s_nop 0
	v_max_f32_e32 v60, 0, v60
	v_mul_f32_e32 v66, v56, v56
	v_max_f32_e32 v56, 0, v61
	v_mul_f32_e32 v61, v57, v57
	v_max_f32_e32 v57, 0, v62
	v_mul_f32_e32 v62, v58, v58
	v_max_f32_e32 v58, 0, v63
	v_mul_f32_e32 v60, v60, v60
	v_mul_f32_e32 v56, v56, v56
	v_max_f32_e32 v59, 0, v59
	v_mul_f32_e32 v57, v57, v57
	v_mul_f32_e32 v58, v58, v58
	v_cvt_pk_bf16_f32 v56, v60, v56
	v_add_co_u32_e32 v60, vcc, s54, v144
	v_max_f32_e32 v48, 0, v48
	v_max_f32_e32 v49, 0, v49
	v_max_f32_e32 v50, 0, v50
	v_mul_f32_e32 v59, v59, v59
	v_cvt_pk_bf16_f32 v57, v57, v58
	v_cvt_pk_bf16_f32 v58, v66, v61
	v_addc_co_u32_e32 v61, vcc, 0, v145, vcc
	v_cvt_pk_bf16_f32 v59, v62, v59
	global_store_dwordx4 v[60:61], v[56:59], off
	v_max_f32_e32 v52, 0, v52
	v_max_f32_e32 v51, 0, v51
	v_mul_f32_e32 v56, v48, v48
	v_max_f32_e32 v48, 0, v53
	v_mul_f32_e32 v53, v49, v49
	v_max_f32_e32 v49, 0, v54
	v_mul_f32_e32 v54, v50, v50
	v_max_f32_e32 v50, 0, v55
	v_mul_f32_e32 v48, v48, v48
	v_mul_f32_e32 v49, v49, v49
	v_mul_f32_e32 v50, v50, v50
	v_max_f32_e32 v40, 0, v40
	v_lshl_add_u64 v[64:65], v[144:145], 0, s[14:15]
	v_mul_f32_e32 v52, v52, v52
	v_mul_f32_e32 v51, v51, v51
	v_cvt_pk_bf16_f32 v48, v52, v48
	v_cvt_pk_bf16_f32 v49, v49, v50
	v_cvt_pk_bf16_f32 v50, v56, v53
	v_max_f32_e32 v41, 0, v41
	v_max_f32_e32 v42, 0, v42
	v_cvt_pk_bf16_f32 v51, v54, v51
	global_store_dwordx4 v[64:65], v[48:51], off offset:256
	s_nop 0
	v_max_f32_e32 v44, 0, v44
	v_mul_f32_e32 v50, v40, v40
	v_max_f32_e32 v40, 0, v45
	v_mul_f32_e32 v45, v41, v41
	v_max_f32_e32 v41, 0, v46
	v_mul_f32_e32 v46, v42, v42
	v_max_f32_e32 v42, 0, v47
	v_mul_f32_e32 v44, v44, v44
	v_mul_f32_e32 v40, v40, v40
	v_max_f32_e32 v43, 0, v43
	v_mul_f32_e32 v41, v41, v41
	v_mul_f32_e32 v42, v42, v42
	v_cvt_pk_bf16_f32 v40, v44, v40
	v_add_co_u32_e32 v44, vcc, s55, v144
	v_max_f32_e32 v32, 0, v32
	v_max_f32_e32 v33, 0, v33
	v_max_f32_e32 v34, 0, v34
	v_mul_f32_e32 v43, v43, v43
	v_cvt_pk_bf16_f32 v41, v41, v42
	v_cvt_pk_bf16_f32 v42, v50, v45
	v_addc_co_u32_e32 v45, vcc, 0, v145, vcc
	v_cvt_pk_bf16_f32 v43, v46, v43
	global_store_dwordx4 v[44:45], v[40:43], off
	v_max_f32_e32 v36, 0, v36
	v_max_f32_e32 v35, 0, v35
	v_mul_f32_e32 v40, v32, v32
	v_max_f32_e32 v32, 0, v37
	v_mul_f32_e32 v37, v33, v33
	v_max_f32_e32 v33, 0, v38
	v_mul_f32_e32 v38, v34, v34
	v_max_f32_e32 v34, 0, v39
	v_mul_f32_e32 v32, v32, v32
	v_mul_f32_e32 v33, v33, v33
	v_mul_f32_e32 v34, v34, v34
	v_max_f32_e32 v24, 0, v24
	v_lshl_add_u64 v[48:49], v[144:145], 0, s[16:17]
	v_mul_f32_e32 v36, v36, v36
	v_mul_f32_e32 v35, v35, v35
	v_cvt_pk_bf16_f32 v32, v36, v32
	v_cvt_pk_bf16_f32 v33, v33, v34
	v_cvt_pk_bf16_f32 v34, v40, v37
	v_max_f32_e32 v25, 0, v25
	v_max_f32_e32 v26, 0, v26
	v_cvt_pk_bf16_f32 v35, v38, v35
	global_store_dwordx4 v[48:49], v[32:35], off offset:256
	s_nop 0
	v_max_f32_e32 v28, 0, v28
	v_mul_f32_e32 v34, v24, v24
	v_max_f32_e32 v24, 0, v29
	v_mul_f32_e32 v29, v25, v25
	v_max_f32_e32 v25, 0, v30
	v_mul_f32_e32 v30, v26, v26
	v_max_f32_e32 v26, 0, v31
	v_mul_f32_e32 v28, v28, v28
	v_mul_f32_e32 v24, v24, v24
	v_max_f32_e32 v27, 0, v27
	v_mul_f32_e32 v25, v25, v25
	v_mul_f32_e32 v26, v26, v26
	v_cvt_pk_bf16_f32 v24, v28, v24
	v_add_co_u32_e32 v28, vcc, s56, v144
	v_max_f32_e32 v16, 0, v16
	v_max_f32_e32 v17, 0, v17
	v_max_f32_e32 v18, 0, v18
	v_mul_f32_e32 v27, v27, v27
	v_cvt_pk_bf16_f32 v25, v25, v26
	v_cvt_pk_bf16_f32 v26, v34, v29
	v_addc_co_u32_e32 v29, vcc, 0, v145, vcc
	v_cvt_pk_bf16_f32 v27, v30, v27
	global_store_dwordx4 v[28:29], v[24:27], off
	v_max_f32_e32 v20, 0, v20
	v_max_f32_e32 v19, 0, v19
	v_mul_f32_e32 v24, v16, v16
	v_max_f32_e32 v16, 0, v21
	v_mul_f32_e32 v21, v17, v17
	v_max_f32_e32 v17, 0, v22
	v_mul_f32_e32 v22, v18, v18
	v_max_f32_e32 v18, 0, v23
	v_mul_f32_e32 v16, v16, v16
	v_mul_f32_e32 v17, v17, v17
	v_mul_f32_e32 v18, v18, v18
	v_max_f32_e32 v8, 0, v8
	v_lshl_add_u64 v[32:33], v[144:145], 0, s[18:19]
	v_mul_f32_e32 v20, v20, v20
	v_mul_f32_e32 v19, v19, v19
	v_cvt_pk_bf16_f32 v16, v20, v16
	v_cvt_pk_bf16_f32 v17, v17, v18
	v_cvt_pk_bf16_f32 v18, v24, v21
	v_max_f32_e32 v9, 0, v9
	v_max_f32_e32 v10, 0, v10
	v_cvt_pk_bf16_f32 v19, v22, v19
	global_store_dwordx4 v[32:33], v[16:19], off offset:256
	s_nop 0
	v_max_f32_e32 v12, 0, v12
	v_mul_f32_e32 v18, v8, v8
	v_max_f32_e32 v8, 0, v13
	v_mul_f32_e32 v13, v9, v9
	v_max_f32_e32 v9, 0, v14
	v_mul_f32_e32 v14, v10, v10
	v_max_f32_e32 v10, 0, v15
	v_mul_f32_e32 v12, v12, v12
	v_mul_f32_e32 v8, v8, v8
	v_max_f32_e32 v11, 0, v11
	v_mul_f32_e32 v9, v9, v9
	v_mul_f32_e32 v10, v10, v10
	v_cvt_pk_bf16_f32 v8, v12, v8
	v_add_co_u32_e32 v12, vcc, s57, v144
	v_max_f32_e32 v0, 0, v0
	v_max_f32_e32 v1, 0, v1
	v_max_f32_e32 v2, 0, v2
	v_mul_f32_e32 v11, v11, v11
	v_cvt_pk_bf16_f32 v9, v9, v10
	v_cvt_pk_bf16_f32 v10, v18, v13
	v_addc_co_u32_e32 v13, vcc, 0, v145, vcc
	v_cvt_pk_bf16_f32 v11, v14, v11
	global_store_dwordx4 v[12:13], v[8:11], off
	v_max_f32_e32 v3, 0, v3
	v_max_f32_e32 v4, 0, v4
	v_mul_f32_e32 v8, v0, v0
	v_max_f32_e32 v0, 0, v5
	v_mul_f32_e32 v5, v1, v1
	v_max_f32_e32 v1, 0, v6
	v_mul_f32_e32 v6, v2, v2
	v_max_f32_e32 v2, 0, v7
	v_lshl_add_u64 v[16:17], v[144:145], 0, s[20:21]
	v_mul_f32_e32 v0, v0, v0
	v_mul_f32_e32 v1, v1, v1
	v_mul_f32_e32 v2, v2, v2
	v_mul_f32_e32 v3, v3, v3
	s_andn2_b64 vcc, exec, s[0:1]
	s_mov_b64 s[0:1], -1
	v_mul_f32_e32 v4, v4, v4
	v_cvt_pk_bf16_f32 v0, v4, v0
	v_cvt_pk_bf16_f32 v1, v1, v2
	v_cvt_pk_bf16_f32 v2, v8, v5
	v_cvt_pk_bf16_f32 v3, v6, v3
	global_store_dwordx4 v[16:17], v[0:3], off offset:256
	s_cbranch_vccnz .LBB0_1462
	s_andn2_b64 vcc, exec, s[6:7]
	s_cbranch_vccnz .LBB0_1461
	s_barrier
	s_branch .LBB0_1461
